# same-layer windows, B window 3 iterations (A=2,P=3,B=3)
# baseline (speedup 1.0000x reference)
; __device__ __forceinline__ int opaque_tid() { int t = threadIdx.x; asm volatile("" : "+v"(t)); return t; }
;     for (int it = 0; it < budget; ++it) {
;         unsigned r = 0; if (lane == 0) r = __hip_atomic_fetch_add(ctr, 2u, __ATOMIC_RELAXED, __HIP_MEMORY_SCOPE_AGENT);
;         r = (unsigned)__builtin_amdgcn_readfirstlane((int)r) + (unsigned)CV_PRO_ITEMS;
;         if (r >= (unsigned)IT_LAYER) break;
;         cv_pair(a, lds, l, (int)r, wave, lane);
;     }
; }
; __global__ void __launch_bounds__(NTHREADS, 2) mk_fwd(Args args) {
;     ...
;             if (l + 1 < DEPTH && !(G >= 256 && bid < 128)) { __syncthreads(); const int tid_ = opaque_tid(); convert_layer_queue(pt, lds, l + 1, cvq, tid_ >> 6, tid_ & 63); }
.LBB0_560:
	v_readlane_b32 s0, v252, 4
	s_cmp_lg_u32 s0, 0x100
	s_cbranch_scc1 .LcvqA_ret
	v_readlane_b32 s0, v252, 0
	v_readlane_b32 s36, v255, 0
	s_cmp_lt_u32 s0, 64
	s_cbranch_scc1 .LcvqA_ret
	s_mov_b32 s64, s36
	v_readlane_b32 s0, v254, 53
	v_readlane_b32 s1, v254, 54
	s_mov_b32 s3, s1
	s_lshl_b32 s2, s36, 6
	s_lshl_b64 s[0:1], s[2:3], 2
	v_readlane_b32 s4, v254, 60
	v_readlane_b32 s5, v254, 61
	s_add_u32 s0, s4, s0
	s_addc_u32 s1, s5, s1
	s_add_u32 s0, s0, 0x8000
	s_addc_u32 s1, s1, 0
	s_add_i32 s2, s36, 0
	s_mul_hi_u32 s33, s2, 0x2c00000
	s_mul_i32 s34, s2, 0x2c00000
	s_mul_hi_u32 s35, s2, 0x1600000
	s_mul_i32 s50, s2, 0x1600000
	s_lshl_b32 s6, s2, 11
	s_mov_b32 s7, s3
	s_lshl_b64 s[8:9], s[2:3], 24
	s_lshl_b64 s[10:11], s[2:3], 23
	s_mul_hi_u32 s51, s2, 0xc00000
	s_mul_i32 s52, s2, 0xc00000
	s_mul_hi_u32 s53, s2, 0x7280000
	s_mul_i32 s54, s2, 0x7280000
	s_mul_hi_u32 s55, s2, 0x3a00000
	v_writelane_b32 v254, s2, 53
	v_mov_b32_e32 v2, v0
	s_mul_i32 s56, s2, 0x3a00000
	v_writelane_b32 v254, s3, 54
	s_waitcnt vmcnt(0) lgkmcnt(0)
	s_barrier
	s_movk_i32 s2, 0x4200
	v_lshrrev_b32_e32 v1, 6, v2
	v_and_b32_e32 v3, 63, v2
	v_readfirstlane_b32 s100, v1
	v_readlane_b32 s101, v252, 0
	s_sub_u32 s101, s101, 64
	s_lshl_b32 s101, s101, 3
	s_add_u32 s100, s100, s101
	s_lshl_b32 s100, s100, 1
	s_add_u32 s100, s100, 0x1800
	v_mul_lo_u32 v1, v1, s2
	v_cmp_eq_u32_e64 s[40:41], 0, v3
	v_add_u32_e32 v3, 0, v1
	v_lshlrev_b32_e32 v1, 2, v2
	v_and_b32_e32 v66, 28, v1
	v_bfe_u32 v1, v2, 3, 3
	v_lshlrev_b32_e32 v2, 3, v2
	v_and_b32_e32 v68, 56, v2
	v_lshl_add_u32 v4, v66, 2, v3
	v_mul_u32_u24_e32 v5, 0x84, v1
	v_mul_u32_u24_e32 v2, 0x84, v68
	v_lshlrev_b32_e32 v6, 2, v1
	v_or_b32_e32 v67, 8, v1
	v_or_b32_e32 v69, 16, v1
	v_or_b32_e32 v71, 24, v1
	v_or_b32_e32 v73, 32, v1
	v_or_b32_e32 v75, 40, v1
	v_or_b32_e32 v77, 48, v1
	v_or_b32_e32 v79, 56, v1
	v_add3_u32 v81, v3, v2, v6
	s_mov_b32 s57, 0x2
	v_add_u32_e32 v83, v4, v5
	s_branch .LcvqA_1381

; __device__ __forceinline__ int opaque_tid() { int t = threadIdx.x; asm volatile("" : "+v"(t)); return t; }
;     for (int it = 0; it < budget; ++it) {
;         unsigned r = 0; if (lane == 0) r = __hip_atomic_fetch_add(ctr, 2u, __ATOMIC_RELAXED, __HIP_MEMORY_SCOPE_AGENT);
;         r = (unsigned)__builtin_amdgcn_readfirstlane((int)r) + (unsigned)CV_PRO_ITEMS;
;         if (r >= (unsigned)IT_LAYER) break;
;         cv_pair(a, lds, l, (int)r, wave, lane);
;     }
; }
; __global__ void __launch_bounds__(NTHREADS, 2) mk_fwd(Args args) {
;     ...
;             if (l + 1 < DEPTH && !(G >= 256 && bid < 128)) { __syncthreads(); const int tid_ = opaque_tid(); convert_layer_queue(pt, lds, l + 1, cvq, tid_ >> 6, tid_ & 63); }
.LBB0_1377:
	s_cmp_eq_u32 s64, 0x63
	v_readlane_b32 s2, v253, 61
	s_cselect_b64 s[0:1], -1, 0
	v_readlane_b32 s3, v253, 62
	s_or_b64 s[0:1], s[2:3], s[0:1]
	v_readlane_b32 s2, v252, 4
	s_cmp_lg_u32 s2, 0x100
	s_cselect_b64 s[2:3], -1, 0
	s_or_b64 s[0:1], s[0:1], s[2:3]
	v_readlane_b32 s28, v254, 55
	s_mov_b32 s36, s64
	s_and_b64 vcc, exec, s[0:1]
	v_readlane_b32 s29, v254, 56
	s_cbranch_vccnz .LBB0_1470
	v_readlane_b32 s0, v254, 53
	v_readlane_b32 s1, v254, 54
	s_mov_b32 s3, s1
	s_lshl_b32 s2, s36, 6
	s_lshl_b64 s[0:1], s[2:3], 2
	v_readlane_b32 s4, v254, 60
	v_readlane_b32 s5, v254, 61
	s_add_u32 s0, s4, s0
	s_addc_u32 s1, s5, s1
	s_add_u32 s0, s0, 0x8000
	s_addc_u32 s1, s1, 0
	s_add_i32 s2, s36, 0
	s_mul_hi_u32 s33, s2, 0x2c00000
	s_mul_i32 s34, s2, 0x2c00000
	s_mul_hi_u32 s35, s2, 0x1600000
	s_mul_i32 s50, s2, 0x1600000
	s_lshl_b32 s6, s2, 11
	s_mov_b32 s7, s3
	s_lshl_b64 s[8:9], s[2:3], 24
	s_lshl_b64 s[10:11], s[2:3], 23
	s_mul_hi_u32 s51, s2, 0xc00000
	s_mul_i32 s52, s2, 0xc00000
	s_mul_hi_u32 s53, s2, 0x7280000
	s_mul_i32 s54, s2, 0x7280000
	s_mul_hi_u32 s55, s2, 0x3a00000
	v_writelane_b32 v254, s2, 53
	v_mov_b32_e32 v2, v0
	s_mul_i32 s56, s2, 0x3a00000
	v_writelane_b32 v254, s3, 54
	s_waitcnt vmcnt(0) lgkmcnt(0)
	s_barrier
	s_movk_i32 s2, 0x4200
	v_lshrrev_b32_e32 v1, 6, v2
	v_and_b32_e32 v3, 63, v2
	v_readfirstlane_b32 s100, v1
	v_readlane_b32 s101, v252, 0
	s_sub_u32 s101, s101, 128
	s_lshl_b32 s101, s101, 3
	s_add_u32 s100, s100, s101
	s_lshl_b32 s100, s100, 1
	s_add_u32 s100, s100, 0x3000
	v_mul_lo_u32 v1, v1, s2
	v_cmp_eq_u32_e64 s[40:41], 0, v3
	v_add_u32_e32 v3, 0, v1
	v_lshlrev_b32_e32 v1, 2, v2
	v_and_b32_e32 v66, 28, v1
	v_bfe_u32 v1, v2, 3, 3
	v_lshlrev_b32_e32 v2, 3, v2
	v_and_b32_e32 v68, 56, v2
	v_lshl_add_u32 v4, v66, 2, v3
	v_mul_u32_u24_e32 v5, 0x84, v1
	v_mul_u32_u24_e32 v2, 0x84, v68
	v_lshlrev_b32_e32 v6, 2, v1
	v_or_b32_e32 v67, 8, v1
	v_or_b32_e32 v69, 16, v1
	v_or_b32_e32 v71, 24, v1
	v_or_b32_e32 v73, 32, v1
	v_or_b32_e32 v75, 40, v1
	v_or_b32_e32 v77, 48, v1
	v_or_b32_e32 v79, 56, v1
	v_add3_u32 v81, v3, v2, v6
	s_mov_b32 s57, 0x3
	v_add_u32_e32 v83, v4, v5
	s_branch .LBB0_1381

; __device__ __forceinline__ int opaque_tid() { int t = threadIdx.x; asm volatile("" : "+v"(t)); return t; }
;     for (int it = 0; it < budget; ++it) {
;         unsigned r = 0; if (lane == 0) r = __hip_atomic_fetch_add(ctr, 2u, __ATOMIC_RELAXED, __HIP_MEMORY_SCOPE_AGENT);
;         r = (unsigned)__builtin_amdgcn_readfirstlane((int)r) + (unsigned)CV_PRO_ITEMS;
;         if (r >= (unsigned)IT_LAYER) break;
;         cv_pair(a, lds, l, (int)r, wave, lane);
;     }
; }
; __global__ void __launch_bounds__(NTHREADS, 2) mk_fwd(Args args) {
;     ...
;             if (l + 1 < DEPTH && !(G >= 256 && bid < 128)) { __syncthreads(); const int tid_ = opaque_tid(); convert_layer_queue(pt, lds, l + 1, cvq, tid_ >> 6, tid_ & 63); }
.LBB0_1843:
	v_readlane_b32 s2, v252, 4
	s_cmp_lg_u32 s2, 0x100
	s_cbranch_scc1 .LcvqB_skip
	v_readlane_b32 s2, v252, 0
	s_cmp_lt_u32 s2, 128
	s_cbranch_scc1 .LcvqB_skip
	s_cmp_gt_u32 s36, 2
	s_cbranch_scc1 .LcvqB_skip
	v_writelane_b32 v255, s0, 8
	v_writelane_b32 v255, s1, 9
	v_writelane_b32 v255, s40, 10
	v_writelane_b32 v255, s41, 11
	s_mov_b32 s64, s36
	v_readlane_b32 s0, v254, 53
	v_readlane_b32 s1, v254, 54
	s_mov_b32 s3, s1
	s_lshl_b32 s2, s36, 6
	s_lshl_b64 s[0:1], s[2:3], 2
	v_readlane_b32 s4, v254, 60
	v_readlane_b32 s5, v254, 61
	s_add_u32 s0, s4, s0
	s_addc_u32 s1, s5, s1
	s_add_u32 s0, s0, 0x8000
	s_addc_u32 s1, s1, 0
	s_add_i32 s2, s36, 1
	s_mul_hi_u32 s33, s2, 0x2c00000
	s_mul_i32 s34, s2, 0x2c00000
	s_mul_hi_u32 s35, s2, 0x1600000
	s_mul_i32 s50, s2, 0x1600000
	s_lshl_b32 s6, s2, 11
	s_mov_b32 s7, s3
	s_lshl_b64 s[8:9], s[2:3], 24
	s_lshl_b64 s[10:11], s[2:3], 23
	s_mul_hi_u32 s51, s2, 0xc00000
	s_mul_i32 s52, s2, 0xc00000
	s_mul_hi_u32 s53, s2, 0x7280000
	s_mul_i32 s54, s2, 0x7280000
	s_mul_hi_u32 s55, s2, 0x3a00000
	v_writelane_b32 v254, s2, 53
	v_mov_b32_e32 v2, v0
	s_mul_i32 s56, s2, 0x3a00000
	v_writelane_b32 v254, s3, 54
	s_waitcnt vmcnt(0) lgkmcnt(0)
	s_barrier
	s_movk_i32 s2, 0x4200
	v_lshrrev_b32_e32 v1, 6, v2
	v_and_b32_e32 v3, 63, v2
	v_readfirstlane_b32 s100, v1
	v_readlane_b32 s101, v252, 0
	s_sub_u32 s101, s101, 128
	s_lshl_b32 s101, s101, 3
	s_add_u32 s100, s100, s101
	s_lshl_b32 s100, s100, 1
	s_add_u32 s100, s100, 0x0
	v_mul_lo_u32 v1, v1, s2
	v_cmp_eq_u32_e64 s[40:41], 0, v3
	v_add_u32_e32 v3, 0, v1
	v_lshlrev_b32_e32 v1, 2, v2
	v_and_b32_e32 v66, 28, v1
	v_bfe_u32 v1, v2, 3, 3
	v_lshlrev_b32_e32 v2, 3, v2
	v_and_b32_e32 v68, 56, v2
	v_lshl_add_u32 v4, v66, 2, v3
	v_mul_u32_u24_e32 v5, 0x84, v1
	v_mul_u32_u24_e32 v2, 0x84, v68
	v_lshlrev_b32_e32 v6, 2, v1
	v_or_b32_e32 v67, 8, v1
	v_or_b32_e32 v69, 16, v1
	v_or_b32_e32 v71, 24, v1
	v_or_b32_e32 v73, 32, v1
	v_or_b32_e32 v75, 40, v1
	v_or_b32_e32 v77, 48, v1
	v_or_b32_e32 v79, 56, v1
	v_add3_u32 v81, v3, v2, v6
	s_mov_b32 s57, 0x3
	v_add_u32_e32 v83, v4, v5
	s_branch .LcvqB_1381
